# gate (g) low-rank GEMM tiles moved from mix_b into the non-latent WGs' scan-phase tail (first read by the post phase)
# speedup vs baseline: 1.0108x; 1.0044x over previous
.LBB0_4:
	v_readlane_b32 s11, v227, 0
	s_lshl_b32 s1, s11, 2
	s_lshl_b32 s20, s76, 2
	s_cmpk_lt_i32 s11, 0
	v_writelane_b32 v227, s1, 9
	s_cselect_b64 s[2:3], -1, 0
	v_writelane_b32 v227, s2, 10
	s_mul_hi_i32 s1, s11, 0x59493e15
	v_mov_b32_e32 v1, 0xb60
	v_writelane_b32 v227, s3, 11
	s_lshr_b32 s2, s1, 31
	s_ashr_i32 s1, s1, 10
	s_add_i32 s2, s1, s2
	s_mul_i32 s1, s2, 0xfffff488
	s_add_i32 s1, s1, s11
	s_cmpk_gt_i32 s1, 0x21f
	s_cselect_b64 s[6:7], -1, 0
	v_writelane_b32 v227, s6, 12
	s_cmpk_gt_u32 s1, 0x31f
	v_sub_co_u32_e32 v1, vcc, s1, v1
	v_writelane_b32 v227, s7, 13
	s_cselect_b64 s[6:7], -1, 0
	v_writelane_b32 v227, s6, 14
	s_cmpk_gt_u32 s1, 0x89f
	v_mov_b32_e32 v2, 0xb68
	v_writelane_b32 v227, s7, 15
	s_cselect_b64 s[6:7], -1, 0
	v_writelane_b32 v227, s6, 16
	s_mul_i32 s0, s77, s76
	s_movk_i32 s77, 0x3ff
	v_writelane_b32 v227, s7, 17
	s_xor_b64 s[6:7], vcc, -1
	v_writelane_b32 v227, s6, 18
	v_sub_co_u32_e32 v2, vcc, s1, v2
	s_nop 0
	v_writelane_b32 v227, s7, 19
	s_xor_b64 s[6:7], vcc, -1
	v_writelane_b32 v227, s6, 20
	s_cmpk_gt_u32 s1, 0xb6f
	s_mov_b32 s89, 0
	v_writelane_b32 v227, s7, 21
	s_cselect_b64 s[6:7], -1, 0
	v_writelane_b32 v227, s6, 22
	s_ashr_i32 s3, s2, 31
	s_lshl_b32 s5, s1, 5
	v_writelane_b32 v227, s7, 23
	s_lshl_b64 s[6:7], s[2:3], 17
	v_writelane_b32 v227, s6, 24
	s_add_i32 s5, s5, 0x7ffe9200
	s_and_b32 s5, s5, 0x7fffffc0
	v_writelane_b32 v227, s7, 25
	s_lshl_b64 s[6:7], s[2:3], 16
	v_writelane_b32 v227, s6, 26
	s_lshl_b32 s8, s2, 1
	s_mov_b64 s[70:71], 0x1000
	v_writelane_b32 v227, s7, 27
	v_writelane_b32 v227, s5, 28
	s_lshl_b32 s5, s11, 6
	s_and_b32 s6, s5, 64
	v_writelane_b32 v227, s6, 29
	v_readfirstlane_b32 s6, v2
	s_lshr_b32 s6, s6, 2
	s_add_i32 s6, s6, s8
	s_ashr_i32 s7, s6, 31
	s_lshl_b64 s[12:13], s[6:7], 16
	v_writelane_b32 v227, s12, 30
	s_lshl_b64 s[6:7], s[6:7], 15
	s_and_b32 s5, s5, 0xc0
	v_writelane_b32 v227, s13, 31
	v_writelane_b32 v227, s6, 32
	s_mov_b64 s[74:75], 0x1200
	v_mov_b32_e32 v154, 0x358637bd
	v_writelane_b32 v227, s7, 33
	v_writelane_b32 v227, s5, 34
	v_readfirstlane_b32 s5, v1
	s_lshr_b32 s5, s5, 2
	s_add_i32 s6, s5, s8
	s_ashr_i32 s7, s6, 31
	s_lshl_b64 s[8:9], s[6:7], 16
	v_writelane_b32 v227, s8, 35
	s_lshl_b64 s[6:7], s[6:7], 15
	s_mul_hi_i32 s5, s2, 0xb00000
	v_writelane_b32 v227, s9, 36
	v_writelane_b32 v227, s6, 37
	v_mov_b32_e32 v1, 0x100
	v_sub_co_u32_e32 v1, vcc, s11, v1
	v_writelane_b32 v227, s7, 38
	v_writelane_b32 v227, s5, 39
	s_mul_i32 s5, s2, 0xb00000
	v_writelane_b32 v227, s5, 40
	s_mul_hi_i32 s5, s2, 0x580000
	v_writelane_b32 v227, s5, 41
	s_mul_i32 s5, s2, 0x580000
	v_writelane_b32 v227, s5, 42
	s_add_i32 s5, s1, 0xf760
	s_and_b32 s6, s5, 0xffff
	s_mul_i32 s6, s6, 0xba2f
	s_lshr_b32 s6, s6, 21
	s_lshl_b32 s7, s6, 6
	s_mul_i32 s6, s6, 44
	s_sub_i32 s5, s5, s6
	s_lshl_b32 s5, s5, 6
	v_writelane_b32 v227, s7, 43
	s_and_b32 s5, s5, 0xffc0
	v_writelane_b32 v227, s5, 44
	s_mul_hi_i32 s5, s2, 0x1600000
	v_writelane_b32 v227, s5, 45
	s_mul_i32 s5, s2, 0x1600000
	v_writelane_b32 v227, s5, 46
	s_lshl_b32 s5, s1, 2
	s_add_i32 s6, s5, 0x7ffff380
	s_and_b32 s6, s6, 0x7fffffc0
	v_writelane_b32 v227, s6, 47
	s_lshl_b32 s6, s1, 6
	s_and_b32 s6, s6, 0x3c0
	v_writelane_b32 v227, s6, 48
	s_lshl_b64 s[6:7], s[2:3], 20
	v_writelane_b32 v227, s6, 49
	s_add_i32 s5, s5, 0x7ffff780
	s_and_b32 s3, s5, 0x7fffffc0
	v_writelane_b32 v227, s7, 50
	v_writelane_b32 v227, s3, 51
	s_mul_hi_i32 s3, s2, 0x880000
	v_writelane_b32 v227, s3, 52
	s_mul_i32 s3, s2, 0x880000
	v_writelane_b32 v227, s3, 53
	s_mul_hi_i32 s3, s2, 0x440000
	v_writelane_b32 v227, s3, 54
	s_mul_i32 s2, s2, 0x440000
	v_writelane_b32 v227, s2, 55
	s_ashr_i32 s2, s1, 31
	s_lshr_b32 s2, s2, 28
	s_add_i32 s2, s1, s2
	s_lshl_b32 s3, s2, 2
	s_and_b32 s2, s2, 0x3fffff0
	s_sub_i32 s1, s1, s2
	s_andn2_b32 s3, s3, 63
	s_lshl_b32 s1, s1, 6
	v_writelane_b32 v227, s3, 56
	s_cmpk_lt_i32 s11, 0x180
	v_writelane_b32 v227, s1, 57
	s_cselect_b64 s[2:3], -1, 0
	s_lshl_b32 s12, s11, 8
	s_lshl_b32 s13, s76, 8
	s_lshr_b32 s14, s11, 3
	v_writelane_b32 v227, s2, 58
	s_cmpk_lt_u32 s11, 0xb00
	s_mov_b32 s26, s13
	v_writelane_b32 v227, s3, 59
	s_cselect_b64 s[2:3], -1, 0
	s_lshl_b32 s1, s11, 3
	v_writelane_b32 v227, s2, 60
	s_and_b32 s30, s1, 56
	s_bfe_u32 s1, s11, 0x30003
	v_writelane_b32 v227, s3, 61
	s_or_b32 s1, s1, s30
	v_writelane_b32 v227, s1, 62
	s_lshr_b32 s1, s11, 6
	v_writelane_b32 v227, s1, 63
	s_lshr_b32 s1, s76, 3
	s_cmpk_lt_u32 s11, 0x200
	v_writelane_b32 v226, s1, 0
	s_cselect_b64 s[2:3], -1, 0
	v_writelane_b32 v226, s2, 1
	s_cmpk_gt_i32 s11, 0x7f
	s_mov_b32 s88, 0x800000
	v_writelane_b32 v226, s3, 2
	s_cselect_b64 s[2:3], -1, 0
	v_writelane_b32 v226, s2, 3
	s_add_i32 s15, s76, 0xffffff80
	s_add_i32 s1, s11, 0xffffff80
	s_and_b32 s5, s11, 0x7fffff80
	v_writelane_b32 v226, s3, 4
	s_and_b64 s[2:3], vcc, exec
	s_cselect_b32 s6, s11, s1
	s_cmpk_lg_i32 s5, 0x100
	s_cselect_b64 s[2:3], -1, 0
	s_cmpk_eq_i32 s5, 0x100
	v_readfirstlane_b32 s5, v1
	s_cselect_b32 s10, s5, s6
	s_cmpk_lg_i32 s76, 0x200
	s_cselect_b64 s[6:7], -1, 0
	s_and_b64 s[8:9], s[6:7], exec
	v_writelane_b32 v226, s15, 5
	s_cselect_b32 s31, s15, 0x180
	s_cselect_b32 s10, s1, s10
	s_mov_b64 s[2:3], -1
	v_writelane_b32 v226, s2, 6
	s_cmpk_lt_i32 s11, 0x100
	v_lshrrev_b32_e32 v1, 20, v0
	v_writelane_b32 v226, s3, 7
	s_cselect_b64 s[2:3], -1, 0
	s_or_b64 s[2:3], s[2:3], s[6:7]
	s_and_b64 s[2:3], s[2:3], exec
	s_cselect_b32 s15, s11, s1
	s_cmpk_lt_u32 s5, 0x80
	s_cselect_b32 s15, s5, s15
	s_cmpk_lt_i32 s15, 0x200
	s_cselect_b64 s[2:3], -1, 0
	s_lshr_b32 s1, s31, 31
	s_add_i32 s1, s31, s1
	s_ashr_i32 s1, s1, 1
	s_movk_i32 s1, 0x100
	s_add_i32 s6, s15, s1
	v_writelane_b32 v226, s2, 8
	s_cmpk_lt_i32 s15, 0x100
	v_lshrrev_b32_e32 v0, 10, v0
	v_writelane_b32 v226, s3, 9
	s_cselect_b64 s[2:3], -1, 0
	v_writelane_b32 v226, s2, 10
	s_cmpk_lt_i32 s15, 0x80
	v_or_b32_e32 v0, v0, v1
	v_writelane_b32 v226, s3, 11
	s_cselect_b64 s[2:3], -1, 0
	v_writelane_b32 v226, s2, 12
	s_bfe_i32 s1, s11, 0x10000
	s_and_b32 s7, s11, 1
	v_writelane_b32 v226, s3, 13
	s_ashr_i32 s2, s11, 5
	s_lshl_b32 s5, s2, 11
	s_and_b32 s3, s1, 0x7ff
	s_lshl_b32 s1, s11, 1
	v_writelane_b32 v226, s5, 14
	s_and_b32 s1, s1, 48
	s_bfe_u32 s8, s11, 0x20001
	s_or_b32 s5, s5, s3
	v_writelane_b32 v226, s1, 15
	s_lshl_b32 s1, s2, 2
	s_cmp_eq_u32 s7, 0
	s_cselect_b32 s16, 1, -1
	v_writelane_b32 v226, s1, 16
	s_mul_i32 s2, s16, 0x300
	v_writelane_b32 v226, s2, 17
	s_mul_i32 s2, s7, 0x900000
	s_mul_i32 s9, s8, 0xc0
	s_or_b32 s2, s2, s9
	v_writelane_b32 v226, s9, 18
	s_addk_i32 s2, 0xff40
	v_writelane_b32 v226, s2, 19
	s_add_i32 s42, s5, 0x1000
	s_mul_i32 s2, s7, 0xc00000
	v_writelane_b32 v226, s2, 20
	s_mul_i32 s5, s42, 0x300
	s_lshl_b32 s83, s16, 3
	v_writelane_b32 v226, s5, 21
	s_add_i32 s5, s83, s42
	s_mul_i32 s9, s5, 0x300
	s_add_i32 s5, s5, s83
	v_writelane_b32 v226, s9, 22
	s_mul_i32 s9, s5, 0x300
	s_add_i32 s5, s5, s83
	v_writelane_b32 v226, s9, 23
	s_mul_i32 s9, s5, 0x300
	s_add_i32 s5, s5, s83
	v_writelane_b32 v226, s9, 24
	s_mulk_i32 s5, 0x300
	s_lshl_b32 s2, s8, 6
	v_writelane_b32 v226, s5, 25
	s_add_i32 s5, s76, s11
	s_cmpk_lt_i32 s11, 0x300
	s_cselect_b64 s[18:19], -1, 0
	v_writelane_b32 v226, s18, 26
	s_cmpk_lt_u32 s11, 0x660
	v_and_or_b32 v0, v0, s77, v131
	v_writelane_b32 v226, s19, 27
	s_cselect_b64 s[18:19], -1, 0
	s_and_b32 s9, s11, 7
	v_writelane_b32 v226, s18, 28
	s_mul_i32 s17, s9, 12
	s_mul_i32 s9, s14, 0xab
	v_writelane_b32 v226, s19, 29
	s_bfe_u32 s9, s9, 0x5000b
	v_writelane_b32 v226, s9, 30
	s_mul_i32 s9, s9, 12
	s_sub_i32 s9, s14, s9
	s_and_b32 s9, s9, 0xff
	v_writelane_b32 v226, s14, 31
	s_add_i32 s9, s17, s9
	v_writelane_b32 v226, s17, 32
	s_cmp_lt_i32 s78, 0
	v_writelane_b32 v226, s9, 33
	s_cselect_b64 s[18:19], -1, 0
	v_writelane_b32 v226, s18, 34
	s_mov_b32 s1, -1
	s_movk_i32 s81, 0x6000
	v_writelane_b32 v226, s19, 35
	v_cmp_eq_u32_e64 s[18:19], 0, v0
	v_cvt_f32_u32_e32 v0, s13
	s_mov_b64 s[24:25], 0x80
	v_writelane_b32 v226, s18, 36
	s_mov_b64 s[36:37], 0x100
	v_rcp_iflag_f32_e32 v0, v0
	v_writelane_b32 v226, s19, 37
	v_readlane_b32 s18, v227, 7
	v_readlane_b32 s19, v227, 8
	s_load_dword s9, s[18:19], 0x230
	s_load_dwordx2 s[22:23], s[18:19], 0x1f8
	v_mul_f32_e32 v0, 0x4f7ffffe, v0
	v_cvt_u32_f32_e32 v0, v0
	s_mov_b64 s[62:63], 0x10080
	s_waitcnt lgkmcnt(0)
	s_mul_i32 s91, s0, s9
	s_add_u32 s40, s22, 0x200
	s_addc_u32 s41, s23, 0
	s_add_u32 s64, s22, 0x1000
	s_addc_u32 s65, s23, 0
	s_add_u32 s38, s22, 0x1100
	s_addc_u32 s39, s23, 0
	s_add_u32 s54, s22, 0x1200
	s_addc_u32 s55, s23, 0
	s_add_u32 s18, s22, 0x1300
	s_addc_u32 s19, s23, 0
	v_writelane_b32 v226, s18, 38
	s_cmp_eq_u32 s4, 15
	s_mov_b64 s[34:35], 0x20080
	v_writelane_b32 v226, s19, 39
	s_cselect_b64 s[18:19], -1, 0
	v_writelane_b32 v226, s18, 40
	s_cmp_eq_u32 s4, 14
	s_mov_b64 s[94:95], 0x30080
	v_writelane_b32 v226, s19, 41
	s_cselect_b64 s[18:19], -1, 0
	v_writelane_b32 v226, s18, 42
	s_cmp_eq_u32 s4, 13
	s_mov_b64 s[96:97], 0x20100
	v_writelane_b32 v226, s19, 43
	s_cselect_b64 s[18:19], -1, 0
	v_writelane_b32 v226, s18, 44
	s_cmp_eq_u32 s4, 12
	s_mov_b64 s[86:87], 0x30100
	v_writelane_b32 v226, s19, 45
	s_cselect_b64 s[18:19], -1, 0
	v_writelane_b32 v226, s18, 46
	s_cmp_eq_u32 s4, 11
	s_mov_b64 s[68:69], 0x40100
	v_writelane_b32 v226, s19, 47
	s_cselect_b64 s[18:19], -1, 0
	v_writelane_b32 v226, s18, 48
	s_cmp_eq_u32 s4, 10
	v_mov_b32_e32 v155, 0x3a27c5ac
	v_writelane_b32 v226, s19, 49
	s_cselect_b64 s[18:19], -1, 0
	v_writelane_b32 v226, s18, 50
	s_cmp_eq_u32 s4, 9
	s_movk_i32 s17, 0xc00
	v_writelane_b32 v226, s19, 51
	s_cselect_b64 s[18:19], -1, 0
	v_writelane_b32 v226, s18, 52
	s_cmp_eq_u32 s4, 8
	s_movk_i32 s82, 0xfefe
	v_writelane_b32 v226, s19, 53
	s_cselect_b64 s[18:19], -1, 0
	v_writelane_b32 v226, s18, 54
	s_cmp_eq_u32 s4, 7
	v_mov_b32_e32 v156, 0x3ca908c9
	v_writelane_b32 v226, s19, 55
	s_cselect_b64 s[18:19], -1, 0
	v_writelane_b32 v226, s18, 56
	s_cmp_eq_u32 s4, 6
	v_mov_b32_e32 v157, 0xbf1f24be
	v_writelane_b32 v226, s19, 57
	s_cselect_b64 s[18:19], -1, 0
	v_writelane_b32 v226, s18, 58
	s_cmp_eq_u32 s4, 5
	v_mov_b32_e32 v158, 0x3e642e9d
	v_writelane_b32 v226, s19, 59
	s_cselect_b64 s[18:19], -1, 0
	v_writelane_b32 v226, s18, 60
	s_cmp_eq_u32 s4, 4
	v_mov_b32_e32 v159, 0x3e91f4c4
	v_writelane_b32 v226, s19, 61
	s_cselect_b64 s[18:19], -1, 0
	v_writelane_b32 v226, s18, 62
	s_cmp_eq_u32 s4, 3
	v_mov_b32_e32 v160, 0x3c0881c4
	v_writelane_b32 v226, s19, 63
	s_cselect_b64 s[18:19], -1, 0
	v_writelane_b32 v225, s18, 0
	s_cmp_eq_u32 s4, 2
	v_mov_b32_e32 v161, 0xbab64f3b
	v_writelane_b32 v225, s19, 1
	s_cselect_b64 s[18:19], -1, 0
	v_writelane_b32 v225, s18, 2
	s_cmp_eq_u32 s4, 1
	s_mov_b32 s80, 0xfffff
	v_writelane_b32 v225, s19, 3
	s_cselect_b64 s[18:19], -1, 0
	v_writelane_b32 v225, s18, 4
	s_cmp_eq_u32 s4, 0
	s_mov_b32 s90, 0x300000
	v_writelane_b32 v225, s19, 5
	s_cselect_b64 s[18:19], -1, 0
	s_lshl_b32 s0, s4, 8
	s_add_u32 s0, s22, s0
	v_writelane_b32 v225, s18, 6
	s_addc_u32 s4, s23, 0
	v_mov_b32_e32 v162, 1
	v_writelane_b32 v225, s19, 7
	s_add_u32 s18, s0, 0x1400
	s_addc_u32 s19, s4, 0
	v_writelane_b32 v225, s18, 8
	v_mov_b32_e32 v163, 0x60
	v_mov_b32_e32 v164, 0x3b3504f3
	v_writelane_b32 v225, s19, 9
	s_add_u32 s18, s0, 0x2400
	s_addc_u32 s19, s4, 0
	v_writelane_b32 v225, s18, 10
	v_bfrev_b32_e32 v165, 60
	v_mov_b32_e32 v166, 0xf149f2ca
	v_writelane_b32 v225, s19, 11
	s_add_u32 s18, s22, 0x3400
	s_addc_u32 s19, s23, 0
	v_writelane_b32 v225, s18, 12
	v_mov_b32_e32 v167, 0x7fc
	v_bfrev_b32_e32 v168, 0.5
	v_writelane_b32 v225, s19, 13
	s_add_u32 s18, s22, 0x3500
	s_addc_u32 s19, s23, 0
	v_writelane_b32 v225, s18, 14
	s_cmpk_lt_u32 s10, 0x200
	s_mov_b64 s[22:23], 0x40080
	v_writelane_b32 v225, s19, 15
	v_writelane_b32 v225, s10, 16
	s_cselect_b64 s[18:19], -1, 0
	v_writelane_b32 v225, s18, 17
	s_lshl_b32 s0, s7, 16
	s_lshl_b32 s4, s8, 14
	v_writelane_b32 v225, s19, 18
	s_or_b32 s0, s0, s4
	v_writelane_b32 v225, s0, 19
	v_writelane_b32 v225, s12, 20
	s_add_i32 s0, s12, s13
	v_writelane_b32 v225, s0, 21
	s_lshl_b32 s0, s76, 10
	v_writelane_b32 v225, s0, 22
	v_writelane_b32 v225, s0, 23
	v_writelane_b32 v225, s0, 24
	v_writelane_b32 v225, s0, 25
	s_mov_b32 s12, s13
	s_mov_b32 s0, s89
	s_and_b64 s[0:1], s[12:13], s[0:1]
	v_writelane_b32 v225, s0, 26
	s_abs_i32 s4, s31
	s_lshl_b32 s33, s76, 9
	v_writelane_b32 v225, s1, 27
	s_sub_i32 s0, 0, s13
	v_mul_lo_u32 v1, s0, v0
	v_mul_hi_u32 v1, v0, v1
	v_add_u32_e32 v133, v0, v1
	v_cvt_f32_u32_e32 v0, s4
	v_writelane_b32 v225, s33, 28
	v_writelane_b32 v225, s33, 29
	s_mov_b32 s1, s13
	v_rcp_iflag_f32_e32 v0, v0
	v_writelane_b32 v225, s0, 30
	s_ashr_i32 s27, s13, 31
	v_mov_b32_e32 v1, 0
	v_mul_f32_e32 v0, 0x4f7ffffe, v0
	v_cvt_u32_f32_e32 v0, v0
	v_writelane_b32 v225, s1, 31
	s_ashr_i32 s0, s6, 31
	s_abs_i32 s1, s6
	s_sub_i32 s6, 0, s4
	v_readfirstlane_b32 s7, v0
	s_mul_i32 s6, s6, s7
	s_mul_hi_u32 s6, s7, s6
	s_add_i32 s7, s7, s6
	s_mul_hi_u32 s6, s1, s7
	s_mul_i32 s6, s6, s4
	v_cvt_f32_u32_e32 v0, s76
	s_sub_i32 s1, s1, s6
	s_sub_i32 s6, s1, s4
	s_cmp_ge_u32 s1, s4
	s_cselect_b32 s1, s6, s1
	v_rcp_iflag_f32_e32 v0, v0
	s_sub_i32 s6, s1, s4
	s_cmp_ge_u32 s1, s4
	s_cselect_b32 s1, s6, s1
	s_xor_b32 s1, s1, s0
	v_mul_f32_e32 v0, 0x4f7ffffe, v0
	s_sub_i32 s10, s1, s0
	v_cvt_u32_f32_e32 v0, v0
	s_cmpk_lt_i32 s10, 0x100
	s_cselect_b64 s[6:7], -1, 0
	v_writelane_b32 v225, s6, 32
	s_sub_i32 s4, 0, s76
	s_mov_b64 s[18:19], 0x50080
	v_writelane_b32 v225, s7, 33
	v_readfirstlane_b32 s6, v0
	s_mul_i32 s4, s4, s6
	s_mul_hi_u32 s4, s6, s4
	s_add_i32 s6, s6, s4
	s_mul_hi_u32 s4, s5, s6
	s_mul_i32 s4, s4, s76
	s_sub_i32 s4, s5, s4
	s_sub_i32 s7, s4, s76
	s_cmp_ge_u32 s4, s76
	s_cselect_b32 s4, s7, s4
	s_sub_i32 s7, s4, s76
	s_cmp_ge_u32 s4, s76
	s_cselect_b32 s4, s7, s4
	s_cmpk_lt_i32 s4, 0xc0
	v_writelane_b32 v225, s4, 34
	s_cselect_b64 s[8:9], -1, 0
	s_abs_i32 s4, s76
	v_cvt_f32_u32_e32 v0, s4
	v_writelane_b32 v225, s8, 35
	s_sub_i32 s7, 0, s4
	v_mov_b32_e32 v169, 0x7f800000
	v_rcp_iflag_f32_e32 v0, v0
	v_writelane_b32 v225, s9, 36
	v_mov_b32_e32 v170, 0x1000
	v_mov_b32_e32 v171, 0xfffff800
	v_mul_f32_e32 v0, 0x4f7ffffe, v0
	v_cvt_u32_f32_e32 v0, v0
	v_mov_b32_e32 v172, 0xffffff00
	v_mov_b32_e32 v173, 0x1800000
	v_mov_b32_e32 v174, 0xffc00000
	v_readfirstlane_b32 s8, v0
	s_mul_i32 s7, s7, s8
	s_mul_hi_u32 s7, s8, s7
	s_add_i32 s8, s8, s7
	s_mul_hi_u32 s7, s8, 0xc0
	s_mul_i32 s7, s7, s4
	s_sub_i32 s7, 0xc0, s7
	s_sub_i32 s9, s7, s4
	s_cmp_ge_u32 s7, s4
	s_cselect_b32 s7, s9, s7
	s_sub_i32 s9, s7, s4
	s_cmp_ge_u32 s7, s4
	s_cselect_b32 s7, s9, s7
	s_sub_i32 s7, s5, s7
	s_mul_hi_u32 s9, s7, s6
	s_mul_i32 s9, s9, s76
	s_sub_i32 s7, s7, s9
	s_sub_i32 s9, s7, s76
	s_cmp_ge_u32 s7, s76
	s_cselect_b32 s7, s9, s7
	s_sub_i32 s9, s7, s76
	s_cmp_ge_u32 s7, s76
	s_cselect_b32 s7, s9, s7
	v_writelane_b32 v225, s7, 37
	s_cmpk_lt_i32 s7, 0xc0
	s_mul_hi_u32 s7, s8, 0x180
	s_mul_i32 s7, s7, s4
	s_cselect_b64 s[12:13], -1, 0
	s_sub_i32 s7, 0x180, s7
	s_sub_i32 s9, s7, s4
	s_cmp_ge_u32 s7, s4
	s_cselect_b32 s7, s9, s7
	s_sub_i32 s9, s7, s4
	s_cmp_ge_u32 s7, s4
	s_cselect_b32 s7, s9, s7
	s_sub_i32 s7, s5, s7
	s_mul_hi_u32 s9, s7, s6
	s_mul_i32 s9, s9, s76
	s_sub_i32 s7, s7, s9
	s_sub_i32 s9, s7, s76
	s_cmp_ge_u32 s7, s76
	s_cselect_b32 s7, s9, s7
	s_sub_i32 s9, s7, s76
	v_writelane_b32 v225, s12, 38
	s_cmp_ge_u32 s7, s76
	s_cselect_b32 s7, s9, s7
	v_writelane_b32 v225, s13, 39
	v_writelane_b32 v225, s7, 40
	s_cmpk_lt_i32 s7, 0xc0
	s_mul_hi_u32 s7, s8, 0x240
	s_mul_i32 s7, s7, s4
	s_cselect_b64 s[12:13], -1, 0
	s_sub_i32 s7, 0x240, s7
	s_sub_i32 s9, s7, s4
	s_cmp_ge_u32 s7, s4
	s_cselect_b32 s7, s9, s7
	s_sub_i32 s9, s7, s4
	s_cmp_ge_u32 s7, s4
	s_cselect_b32 s7, s9, s7
	s_sub_i32 s7, s5, s7
	s_mul_hi_u32 s9, s7, s6
	s_mul_i32 s9, s9, s76
	s_sub_i32 s7, s7, s9
	s_sub_i32 s9, s7, s76
	s_cmp_ge_u32 s7, s76
	s_cselect_b32 s7, s9, s7
	s_sub_i32 s9, s7, s76
	v_writelane_b32 v225, s12, 41
	s_cmp_ge_u32 s7, s76
	s_cselect_b32 s7, s9, s7
	v_writelane_b32 v225, s13, 42
	v_writelane_b32 v225, s7, 43
	s_cmpk_lt_i32 s7, 0xc0
	s_mul_hi_u32 s7, s8, 0x300
	s_mul_i32 s7, s7, s4
	s_cselect_b64 s[12:13], -1, 0
	s_sub_i32 s7, 0x300, s7
	s_sub_i32 s8, s7, s4
	s_cmp_ge_u32 s7, s4
	s_cselect_b32 s7, s8, s7
	s_sub_i32 s8, s7, s4
	s_cmp_ge_u32 s7, s4
	s_cselect_b32 s4, s8, s7
	s_sub_i32 s4, s5, s4
	s_mul_hi_u32 s6, s4, s6
	s_mul_i32 s6, s6, s76
	s_sub_i32 s4, s4, s6
	s_sub_i32 s6, s4, s76
	s_cmp_ge_u32 s4, s76
	s_cselect_b32 s4, s6, s4
	s_sub_i32 s6, s4, s76
	s_cmp_ge_u32 s4, s76
	v_writelane_b32 v225, s12, 44
	s_cselect_b32 s4, s6, s4
	s_cmpk_lt_i32 s4, 0xc0
	v_writelane_b32 v225, s13, 45
	v_writelane_b32 v225, s4, 46
	s_cselect_b64 s[6:7], -1, 0
	v_writelane_b32 v225, s6, 47
	s_lshl_b32 s4, s5, 5
	s_add_i32 s4, s4, 0x7ffe9200
	v_writelane_b32 v225, s7, 48
	v_writelane_b32 v225, s4, 49
	s_lshl_b32 s4, s76, 5
	v_writelane_b32 v225, s4, 50
	s_lshl_b32 s4, s5, 2
	s_add_i32 s4, s4, 0x7ffff380
	v_writelane_b32 v225, s4, 51
	s_lshl_b32 s4, s5, 6
	v_writelane_b32 v225, s4, 52
	s_lshl_b32 s4, s76, 6
	v_writelane_b32 v225, s4, 53
	s_lshl_b64 s[4:5], s[26:27], 2
	v_writelane_b32 v225, s4, 54
	s_lshl_b64 s[28:29], s[26:27], 1
	v_mbcnt_lo_u32_b32 v0, -1, 0
	v_writelane_b32 v225, s5, 55
	s_lshl_b32 s4, s11, 18
	v_writelane_b32 v225, s4, 56
	s_lshl_b32 s4, s76, 20
	s_bitcmp1_b32 s15, 0
	v_writelane_b32 v225, s4, 57
	s_cselect_b64 s[4:5], -1, 0
	v_writelane_b32 v225, s4, 58
	s_bitcmp1_b32 s31, 0
	v_mbcnt_hi_u32_b32 v150, -1, v0
	v_writelane_b32 v225, s5, 59
	s_cselect_b64 s[4:5], -1, 0
	v_writelane_b32 v225, s4, 60
	s_bitcmp1_b32 s10, 0
	v_and_b32_e32 v0, 64, v150
	v_writelane_b32 v225, s5, 61
	v_writelane_b32 v225, s10, 62
	s_cselect_b64 s[4:5], -1, 0
	s_lshl_b32 s1, s1, 5
	s_lshl_b32 s0, s0, 5
	v_writelane_b32 v225, s4, 63
	s_sub_i32 s0, s1, s0
	s_ashr_i32 s21, s20, 31
	v_writelane_b32 v224, s5, 0
	v_writelane_b32 v224, 0, 40
	v_writelane_b32 v224, 0, 42
	v_writelane_b32 v224, s0, 1
	s_lshl_b32 s0, s31, 5
	v_writelane_b32 v224, s0, 2
	v_writelane_b32 v224, s15, 3
	s_lshl_b32 s0, s15, 5
	v_writelane_b32 v224, s0, 4
	s_or_b32 s0, s3, 0x1000
	v_writelane_b32 v224, s0, 5
	v_writelane_b32 v224, s16, 6
	s_lshl_b32 s0, s16, 5
	v_writelane_b32 v224, s0, 7
	s_lshl_b32 s0, s11, 4
	v_writelane_b32 v224, s0, 8
	s_lshl_b32 s0, s76, 4
	v_writelane_b32 v224, s0, 9
	s_lshl_b64 s[0:1], s[20:21], 2
	v_writelane_b32 v224, s0, 10
	v_xor_b32_e32 v151, 16, v150
	v_add_u32_e32 v152, 64, v0
	v_writelane_b32 v224, s1, 11
	s_lshl_b64 s[0:1], s[20:21], 12
	v_writelane_b32 v224, s0, 12
	v_xor_b32_e32 v153, 32, v150
	s_mov_b64 s[10:11], 0x10100
	v_writelane_b32 v224, s1, 13
	s_mov_b32 s0, s20
	v_writelane_b32 v224, s0, 14
	s_mov_b32 s5, 0x100000
	v_mov_b32_e32 v175, 0x7fc00000
	v_writelane_b32 v224, s1, 15
	s_lshl_b64 s[0:1], s[20:21], 11
	v_writelane_b32 v224, s0, 16
	v_mov_b32_e32 v176, 0x461c4000
	v_mov_b32_e32 v177, 0x37000000
	v_writelane_b32 v224, s1, 17
	s_lshl_b32 s0, s2, 2
	v_writelane_b32 v224, s0, 18
	v_writelane_b32 v224, s30, 19
	v_writelane_b32 v224, s31, 20
	v_writelane_b32 v224, s42, 21
	v_writelane_b32 v224, s83, 22
	v_writelane_b32 v224, s91, 23
	v_writelane_b32 v224, s40, 24
	s_mov_b32 s0, 0x7f800000
	s_mov_b32 s1, 0x18000
	v_writelane_b32 v224, s41, 25
	v_writelane_b32 v224, s64, 26
	v_not_b32_e32 v178, 63
	v_not_b32_e32 v179, 31
	v_writelane_b32 v224, s65, 27
	v_writelane_b32 v224, s54, 28
	v_mov_b32_e32 v130, v1
	v_mov_b32_e32 v132, v1
	v_writelane_b32 v224, s55, 29
	v_writelane_b32 v224, s38, 30
	s_mov_b32 s31, s42
	s_nop 0
	v_writelane_b32 v224, s39, 31
	v_writelane_b32 v224, s28, 32
	s_nop 1
	v_writelane_b32 v224, s29, 33
	s_branch .LBB0_7

.LBB0_275:
	v_readlane_b32 s12, v227, 0
	s_nop 0
	s_add_i32 s12, s12, 0xffffff80
	s_cmpk_lt_u32 s12, 0xc0
	s_cbranch_scc0 .Lg4_ret
	v_writelane_b32 v224, s12, 43
	s_mov_b32 s2, 1
	v_writelane_b32 v224, s2, 42
	v_readlane_b32 s28, v224, 34
	v_readlane_b32 s29, v224, 35
	v_readlane_b32 s38, v224, 36
	s_mov_b32 s16, 0x1ffffc0
	s_mov_b64 s[52:53], 0x2000
	s_mov_b64 s[40:41], 0x4000
	s_mov_b64 s[42:43], 0x6000
	s_mov_b64 s[56:57], 0x2080
	s_mov_b64 s[58:59], 0x4080
	s_mov_b64 s[72:73], 0x6080
	s_movk_i32 s66, 0x2400
	s_movk_i32 s67, 0x90
	s_waitcnt vmcnt(0) lgkmcnt(0)
	s_barrier
	s_branch .Lg4_entry

.LBB0_304:
	v_readlane_b32 s2, v225, 47
	v_readlane_b32 s3, v225, 48
	v_readlane_b32 s28, v224, 34
	s_andn2_b64 vcc, exec, s[2:3]
	s_mov_b64 s[40:41], 0x4000
	s_mov_b64 s[42:43], 0x6000
	v_readlane_b32 s29, v224, 35
	s_branch .LBB0_307
.Lg4_entry:
	s_load_dwordx2 s[2:3], s[28:29], 0x130
	s_ashr_i32 s39, s38, 31
	s_lshl_b64 s[6:7], s[38:39], 16
	v_readlane_b32 s12, v224, 43
	s_waitcnt lgkmcnt(0)
	s_add_u32 s8, s2, s6
	s_addc_u32 s9, s3, s7
	s_load_dwordx2 s[2:3], s[28:29], 0x1a0
	s_waitcnt vmcnt(0)

.LBB0_307:
	v_readlane_b32 s2, v224, 42
	s_nop 0
	s_cmp_eq_u32 s2, 0
	s_cbranch_scc1 .Lg4_norm
	v_writelane_b32 v224, 0, 42
	s_branch .Lg4_ret
